# opt22: opt19 + L2 prefetch (one dword per line) of the next attention unit's first two K/V tiles issued in the current unit's last iteration (diff) / loop preheader (windowed)
# speedup vs baseline: 1.0073x; 1.0073x over previous
; template <bool SWA>
; __device__ __forceinline__ void unit(LAS unsigned char* lds, const bf16_t* PROJ, const bf16_t* KT, const bf16_t* VT, bf16_t* OB, int opitch, int ocol, int b, int head, int qb, float slope2, float m_init, float lam, const float* subg) {
;     ...
;     const char* Kg = (const char*)(KT + (SWA ? (size_t)(b * 4 + kvh) * SEQ * 64 : (size_t)(b * 8 + head) * SEQ * 128));
;     const char* Vg = (const char*)(VT + (SWA ? (size_t)(b * 4 + kvh) * SEQ * 64 : (size_t)(b * 8 + head) * SEQ * 128));
; __global__ void __launch_bounds__(512, 2) fwd_megakernel(Args a) {
;     ...
;         for (int i = 0; i < 8; ++i) {
;             const int id = i * G + xvcu; if (id >= 2048) break;
;             int bh = id >> 4; const int qb = id & 15; int b = bh >> 3, h = bh & 7;
;             if (G == 256) { const int v4 = xvcu >> 4; h = (i + v4) & 7; b = 2 * i + (v4 >> 3); }
;             const float slope2 = exp2f(-(float)(h + 1)) * LOG2E;
;             att::unit<false>(lds, PROJ, KD, VT, PROJ, PP, C_DQ + h * 128, b, h, qb, slope2, -INFINITY, lam, a.da_subnorm);
.LBB0_917:
	v_readlane_b32 s84, v255, 20
	s_cmp_lg_u32 s84, 0
	s_cbranch_scc0 .Ldk_nopf
	s_lshr_b32 s84, s69, 11
	s_add_i32 s84, s84, 2
	s_lshl_b32 s84, s84, 3
	s_lshr_b32 s85, s68, 7
	s_add_i32 s85, s85, 1
	s_and_b32 s85, s85, 7
	s_add_i32 s84, s84, s85
	s_lshl_b32 s84, s84, 19
	s_lshl_b32 s85, s16, 15
	s_add_i32 s84, s84, s85
	s_add_i32 s84, s84, 0xffff8000
	v_readlane_b32 s86, v254, 59
	v_readlane_b32 s87, v254, 60
	v_readlane_b32 s88, v254, 57
	s_sub_u32 s88, s88, s86
	s_add_i32 s88, s88, 0x8000
	s_add_u32 s86, s86, s84
	s_addc_u32 s87, s87, 0
	v_lshrrev_b32_e32 v247, 8, v246
	v_xor_b32_e32 v247, 1, v247
	v_mul_lo_u32 v247, v247, s88
	v_lshl_add_u32 v247, v246, 7, v247
	global_load_dword v247, v247, s[86:87]

; template <bool SWA>
; __device__ __forceinline__ void unit(LAS unsigned char* lds, const bf16_t* PROJ, const bf16_t* KT, const bf16_t* VT, bf16_t* OB, int opitch, int ocol, int b, int head, int qb, float slope2, float m_init, float lam, const float* subg) {
;     ...
;     const char* Kg = (const char*)(KT + (SWA ? (size_t)(b * 4 + kvh) * SEQ * 64 : (size_t)(b * 8 + head) * SEQ * 128));
;     const char* Vg = (const char*)(VT + (SWA ? (size_t)(b * 4 + kvh) * SEQ * 64 : (size_t)(b * 8 + head) * SEQ * 128));
; __global__ void __launch_bounds__(512, 2) fwd_megakernel(Args a) {
;     ...
;         for (int i = 0; i < 8; ++i) {
;             const int id = i * G + xvcu; if (id >= 2048) break;
;             const int qb = id & 31, bk = id >> 5, b = bk >> 2, kvh = bk & 3;
;             att::unit<true>(lds, PROJ, KS, VTS, PROJ, PP, C_SQ + kvh * 256, b, kvh, qb, 0.f, 0.f, 0.f, a.swa_sink);
.Lsq_nopf:
	s_cmp_lg_u32 s32, 0
	s_cbranch_scc0 .Lsk_nopf
	s_add_i32 s100, s29, -2
	s_lshl_b32 s100, s100, 13
	s_add_i32 s100, s100, 0x1fc000
	s_sub_u32 s101, s10, s78
	s_add_i32 s101, s101, 0x4000
	s_add_u32 s98, s78, s100
	s_addc_u32 s99, s79, 0
	v_bfe_u32 v248, v246, 7, 1
	v_xor_b32_e32 v248, 1, v248
	v_mul_lo_u32 v248, v248, s101
	v_and_b32_e32 v249, 0xff, v246
	v_lshl_add_u32 v248, v249, 7, v248
	global_load_dword v248, v248, s[98:99]
